# P10 copy order hardened against store-data overwrite; Wo-epilogue gains kept in registers; q/k/v-up epilogue hoists reverted after intermittent launch-to-launch mismatches
# baseline (speedup 1.0000x reference)
; DI void norm_row_bf16_to_f32(const bf16_t* xrow, const float* g, float* orow, int lane) {
;     u32x4 v[4]; float s = 0.f;
; #pragma unroll
;     for (int j = 0; j < 4; ++j) {
;         v[j] = *((const u32x4*)xrow + lane + 64 * j);
; __global__ void __launch_bounds__(NTHREADS, 2) fwd_megakernel(Params p) {
;     ...
;         for (int m = gw; m < T_; m += NGW) norm_row_bf16_to_f32(HN + (size_t)m * DM, p.in[19], p.out + (size_t)m * DM, lane);
.LBB0_1162:
	s_waitcnt vmcnt(8)
	v_mov_b32_e32 v26, v136
	v_mov_b32_e32 v27, v137
	v_mov_b32_e32 v28, v138
	v_mov_b32_e32 v29, v139
	v_mov_b32_e32 v30, v140
	v_mov_b32_e32 v31, v141
	v_mov_b32_e32 v32, v142
	v_mov_b32_e32 v33, v143
	s_nop 7
	v_mov_b32_e32 v18, v128
	v_mov_b32_e32 v19, v129
	v_mov_b32_e32 v20, v130
	v_mov_b32_e32 v21, v131
	v_mov_b32_e32 v22, v132
	v_mov_b32_e32 v23, v133
	v_mov_b32_e32 v24, v134
	v_mov_b32_e32 v25, v135
	s_add_i32 s4, s4, s58
	s_cmpk_gt_i32 s4, 0x7fff
	s_cbranch_scc1 .Lp10_nopf
	global_load_dwordx4 v[128:131], v[8:9], off
	global_load_dwordx4 v[132:135], v[8:9], off offset:-3072
	global_load_dwordx4 v[136:139], v[8:9], off offset:-2048
	global_load_dwordx4 v[140:143], v[8:9], off offset:-1024
	v_lshl_add_u64 v[8:9], v[8:9], 0, s[2:3]
